# rms phase: two rows in flight per wave, DPP row reduction
# baseline (speedup 1.0000x reference)
; #define GAS __attribute__((address_space(1)))
; __device__ __forceinline__ unsigned cvt_pk_bf16(float lo, float hi) { unsigned r; asm("v_cvt_pk_bf16_f32 %0, %1, %2" : "=v"(r) : "v"(lo), "v"(hi)); return r; }
; __device__ __forceinline__ float wave_sum(float v) { return sum_x32(sum_row32(v)); }
; __device__ __forceinline__ void rms_phase(const gfl* x, const gfl* g, gbf* out, int gw, int NGW, int lane) {
;     ...
;     for (int m = gw; m < MG; m += NGW) {
;         const int mn = m + NGW < MG ? m + NGW : m;
;         { const GAS f32x4* xr = (const GAS f32x4*)(x + (size_t)mn * DM) + lane;
; #pragma unroll
;           for (int j = 0; j < 4; ++j) vn[j] = xr[64 * j]; }
;         float s = 0.f;
; #pragma unroll
;         for (int j = 0; j < 4; ++j) s += (v[j].x * v[j].x + v[j].y * v[j].y) + (v[j].z * v[j].z + v[j].w * v[j].w);
;         const float rstd = __builtin_amdgcn_rsqf(wave_sum(s) * (1.f / DM) + EPS);
;         GAS unsigned long long* o8 = (GAS unsigned long long*)(out + (size_t)m * DM) + lane;
; #pragma unroll
;         for (int j = 0; j < 4; ++j) { const f32x4 w = v[j] * rstd * gv[j]; o8[64 * j] = (unsigned long long)cvt_pk_bf16(w.x, w.y) | ((unsigned long long)cvt_pk_bf16(w.z, w.w) << 32); }
; #pragma unroll
;         for (int j = 0; j < 4; ++j) v[j] = vn[j];
;     }
.LBB0_130:
	s_add_i32 s2, s8, s4
	s_cmp_lt_i32 s2, 0x10000
	s_cselect_b32 s10, s2, s8
	s_ashr_i32 s11, s10, 31
	s_lshl_b64 s[0:1], s[10:11], 12
	v_lshl_add_u64 v[72:73], v[34:35], 0, s[0:1]
	global_load_dwordx4 v[56:59], v[72:73], off
	global_load_dwordx4 v[60:63], v[72:73], off offset:1024
	global_load_dwordx4 v[64:67], v[72:73], off offset:2048
	global_load_dwordx4 v[68:71], v[72:73], off offset:3072
	s_waitcnt vmcnt(4)
	v_mul_f32_e32 v82, v22, v22
	v_mul_f32_e32 v83, v23, v23
	v_fmac_f32_e32 v82, v24, v24
	v_fmac_f32_e32 v83, v25, v25
	v_fmac_f32_e32 v82, v30, v30
	v_fmac_f32_e32 v83, v31, v31
	v_fmac_f32_e32 v82, v32, v32
	v_fmac_f32_e32 v83, v33, v33
	v_fmac_f32_e32 v82, v26, v26
	v_fmac_f32_e32 v83, v27, v27
	v_fmac_f32_e32 v82, v28, v28
	v_fmac_f32_e32 v83, v29, v29
	v_fmac_f32_e32 v82, v18, v18
	v_fmac_f32_e32 v83, v19, v19
	v_fmac_f32_e32 v82, v20, v20
	v_fmac_f32_e32 v83, v21, v21
	v_add_f32_e32 v82, v82, v83
	s_nop 1
	v_add_f32_dpp v82, v82, v82 row_ror:1 row_mask:0xf bank_mask:0xf
	s_nop 1
	v_add_f32_dpp v82, v82, v82 row_ror:2 row_mask:0xf bank_mask:0xf
	s_nop 1
	v_add_f32_dpp v82, v82, v82 row_ror:4 row_mask:0xf bank_mask:0xf
	s_nop 1
	v_add_f32_dpp v82, v82, v82 row_ror:8 row_mask:0xf bank_mask:0xf
	ds_swizzle_b32 v83, v82 offset:swizzle(SWAP,16)
	s_waitcnt lgkmcnt(0)
	v_add_f32_e32 v82, v82, v83
	v_mov_b32_e32 v83, v82
	s_nop 1
	v_permlane32_swap_b32_e32 v82, v83
	v_add_f32_e32 v82, v82, v83
	v_fmamk_f32 v82, v82, 0x3a800000, v218
	v_rsq_f32_e32 v82, v82
	s_nop 0
	v_pk_mul_f32 v[84:85], v[22:23], v[82:83] op_sel_hi:[1,0]
	v_pk_mul_f32 v[84:85], v[2:3], v[84:85]
	v_pk_mul_f32 v[86:87], v[24:25], v[82:83] op_sel_hi:[1,0]
	v_pk_mul_f32 v[86:87], v[4:5], v[86:87]
	v_cvt_pk_bf16_f32 v74, v84, v85
	v_cvt_pk_bf16_f32 v75, v86, v87
	v_pk_mul_f32 v[84:85], v[30:31], v[82:83] op_sel_hi:[1,0]
	v_pk_mul_f32 v[84:85], v[6:7], v[84:85]
	v_pk_mul_f32 v[86:87], v[32:33], v[82:83] op_sel_hi:[1,0]
	v_pk_mul_f32 v[86:87], v[8:9], v[86:87]
	v_cvt_pk_bf16_f32 v76, v84, v85
	v_cvt_pk_bf16_f32 v77, v86, v87
	v_pk_mul_f32 v[84:85], v[26:27], v[82:83] op_sel_hi:[1,0]
	v_pk_mul_f32 v[84:85], v[10:11], v[84:85]
	v_pk_mul_f32 v[86:87], v[28:29], v[82:83] op_sel_hi:[1,0]
	v_pk_mul_f32 v[86:87], v[12:13], v[86:87]
	v_cvt_pk_bf16_f32 v78, v84, v85
	v_cvt_pk_bf16_f32 v79, v86, v87
	v_pk_mul_f32 v[84:85], v[18:19], v[82:83] op_sel_hi:[1,0]
	v_pk_mul_f32 v[84:85], v[14:15], v[84:85]
	v_pk_mul_f32 v[86:87], v[20:21], v[82:83] op_sel_hi:[1,0]
	v_pk_mul_f32 v[86:87], v[16:17], v[86:87]
	v_cvt_pk_bf16_f32 v80, v84, v85
	v_cvt_pk_bf16_f32 v81, v86, v87
	s_add_i32 s2, s8, s4
	s_add_i32 s2, s2, s4
	s_cmp_lt_i32 s2, 0x10000
	s_cselect_b32 s10, s2, s8
	s_ashr_i32 s11, s10, 31
	s_lshl_b64 s[0:1], s[10:11], 12
	v_lshl_add_u64 v[72:73], v[34:35], 0, s[0:1]
	global_load_dwordx4 v[22:25], v[72:73], off
	global_load_dwordx4 v[30:33], v[72:73], off offset:1024
	global_load_dwordx4 v[26:29], v[72:73], off offset:2048
	global_load_dwordx4 v[18:21], v[72:73], off offset:3072
	global_store_dwordx2 v[36:37], v[74:75], off offset:-1024
	global_store_dwordx2 v[36:37], v[76:77], off offset:-512
	global_store_dwordx2 v[36:37], v[78:79], off
	global_store_dwordx2 v[36:37], v[80:81], off offset:512
	v_lshl_add_u64 v[36:37], v[36:37], 0, s[6:7]
	s_add_i32 s2, s8, s4
	s_cmp_lt_i32 s2, 0x10000
	s_cbranch_scc0 .Lrms_done
	s_waitcnt vmcnt(8)
	s_mov_b32 s8, s2
	v_mul_f32_e32 v82, v56, v56
	v_mul_f32_e32 v83, v57, v57
	v_fmac_f32_e32 v82, v58, v58
	v_fmac_f32_e32 v83, v59, v59
	v_fmac_f32_e32 v82, v60, v60
	v_fmac_f32_e32 v83, v61, v61
	v_fmac_f32_e32 v82, v62, v62
	v_fmac_f32_e32 v83, v63, v63
	v_fmac_f32_e32 v82, v64, v64
	v_fmac_f32_e32 v83, v65, v65
	v_fmac_f32_e32 v82, v66, v66
	v_fmac_f32_e32 v83, v67, v67
	v_fmac_f32_e32 v82, v68, v68
	v_fmac_f32_e32 v83, v69, v69
	v_fmac_f32_e32 v82, v70, v70
	v_fmac_f32_e32 v83, v71, v71
	v_add_f32_e32 v82, v82, v83
	s_nop 1
	v_add_f32_dpp v82, v82, v82 row_ror:1 row_mask:0xf bank_mask:0xf
	s_nop 1
	v_add_f32_dpp v82, v82, v82 row_ror:2 row_mask:0xf bank_mask:0xf
	s_nop 1
	v_add_f32_dpp v82, v82, v82 row_ror:4 row_mask:0xf bank_mask:0xf
	s_nop 1
	v_add_f32_dpp v82, v82, v82 row_ror:8 row_mask:0xf bank_mask:0xf
	ds_swizzle_b32 v83, v82 offset:swizzle(SWAP,16)
	s_waitcnt lgkmcnt(0)
	v_add_f32_e32 v82, v82, v83
	v_mov_b32_e32 v83, v82
	s_nop 1
	v_permlane32_swap_b32_e32 v82, v83
	v_add_f32_e32 v82, v82, v83
	v_fmamk_f32 v82, v82, 0x3a800000, v218
	v_rsq_f32_e32 v82, v82
	s_nop 0
	v_pk_mul_f32 v[84:85], v[56:57], v[82:83] op_sel_hi:[1,0]
	v_pk_mul_f32 v[84:85], v[2:3], v[84:85]
	v_pk_mul_f32 v[86:87], v[58:59], v[82:83] op_sel_hi:[1,0]
	v_pk_mul_f32 v[86:87], v[4:5], v[86:87]
	v_cvt_pk_bf16_f32 v74, v84, v85
	v_cvt_pk_bf16_f32 v75, v86, v87
	v_pk_mul_f32 v[84:85], v[60:61], v[82:83] op_sel_hi:[1,0]
	v_pk_mul_f32 v[84:85], v[6:7], v[84:85]
	v_pk_mul_f32 v[86:87], v[62:63], v[82:83] op_sel_hi:[1,0]
	v_pk_mul_f32 v[86:87], v[8:9], v[86:87]
	v_cvt_pk_bf16_f32 v76, v84, v85
	v_cvt_pk_bf16_f32 v77, v86, v87
	v_pk_mul_f32 v[84:85], v[64:65], v[82:83] op_sel_hi:[1,0]
	v_pk_mul_f32 v[84:85], v[10:11], v[84:85]
	v_pk_mul_f32 v[86:87], v[66:67], v[82:83] op_sel_hi:[1,0]
	v_pk_mul_f32 v[86:87], v[12:13], v[86:87]
	v_cvt_pk_bf16_f32 v78, v84, v85
	v_cvt_pk_bf16_f32 v79, v86, v87
	v_pk_mul_f32 v[84:85], v[68:69], v[82:83] op_sel_hi:[1,0]
	v_pk_mul_f32 v[84:85], v[14:15], v[84:85]
	v_pk_mul_f32 v[86:87], v[70:71], v[82:83] op_sel_hi:[1,0]
	v_pk_mul_f32 v[86:87], v[16:17], v[86:87]
	v_cvt_pk_bf16_f32 v80, v84, v85
	v_cvt_pk_bf16_f32 v81, v86, v87
	s_add_i32 s2, s8, s4
	s_add_i32 s2, s2, s4
	s_cmp_lt_i32 s2, 0x10000
	s_cselect_b32 s10, s2, s8
	s_ashr_i32 s11, s10, 31
	s_lshl_b64 s[0:1], s[10:11], 12
	v_lshl_add_u64 v[72:73], v[34:35], 0, s[0:1]
	global_load_dwordx4 v[56:59], v[72:73], off
	global_load_dwordx4 v[60:63], v[72:73], off offset:1024
	global_load_dwordx4 v[64:67], v[72:73], off offset:2048
	global_load_dwordx4 v[68:71], v[72:73], off offset:3072
	global_store_dwordx2 v[36:37], v[74:75], off offset:-1024
	global_store_dwordx2 v[36:37], v[76:77], off offset:-512
	global_store_dwordx2 v[36:37], v[78:79], off
	global_store_dwordx2 v[36:37], v[80:81], off offset:512
	v_lshl_add_u64 v[36:37], v[36:37], 0, s[6:7]
	s_add_i32 s8, s8, s4
	s_cmp_lt_i32 s8, 0x10000
	s_cbranch_scc0 .Lrms_done
; #define GAS __attribute__((address_space(1)))
; __device__ __forceinline__ unsigned cvt_pk_bf16(float lo, float hi) { unsigned r; asm("v_cvt_pk_bf16_f32 %0, %1, %2" : "=v"(r) : "v"(lo), "v"(hi)); return r; }
; __device__ __forceinline__ float wave_sum(float v) { return sum_x32(sum_row32(v)); }
; __device__ __forceinline__ void rms_phase(const gfl* x, const gfl* g, gbf* out, int gw, int NGW, int lane) {
;     ...
;     for (int m = gw; m < MG; m += NGW) {
;         const int mn = m + NGW < MG ? m + NGW : m;
;         { const GAS f32x4* xr = (const GAS f32x4*)(x + (size_t)mn * DM) + lane;
; #pragma unroll
;           for (int j = 0; j < 4; ++j) vn[j] = xr[64 * j]; }
;         float s = 0.f;
; #pragma unroll
;         for (int j = 0; j < 4; ++j) s += (v[j].x * v[j].x + v[j].y * v[j].y) + (v[j].z * v[j].z + v[j].w * v[j].w);
;         const float rstd = __builtin_amdgcn_rsqf(wave_sum(s) * (1.f / DM) + EPS);
;         GAS unsigned long long* o8 = (GAS unsigned long long*)(out + (size_t)m * DM) + lane;
; #pragma unroll
;         for (int j = 0; j < 4; ++j) { const f32x4 w = v[j] * rstd * gv[j]; o8[64 * j] = (unsigned long long)cvt_pk_bf16(w.x, w.y) | ((unsigned long long)cvt_pk_bf16(w.z, w.w) << 32); }
; #pragma unroll
;         for (int j = 0; j < 4; ++j) v[j] = vn[j];
;     }
.Lrms_loop:
	s_waitcnt vmcnt(12)
	v_mul_f32_e32 v82, v22, v22
	v_mul_f32_e32 v83, v23, v23
	v_fmac_f32_e32 v82, v24, v24
	v_fmac_f32_e32 v83, v25, v25
	v_fmac_f32_e32 v82, v30, v30
	v_fmac_f32_e32 v83, v31, v31
	v_fmac_f32_e32 v82, v32, v32
	v_fmac_f32_e32 v83, v33, v33
	v_fmac_f32_e32 v82, v26, v26
	v_fmac_f32_e32 v83, v27, v27
	v_fmac_f32_e32 v82, v28, v28
	v_fmac_f32_e32 v83, v29, v29
	v_fmac_f32_e32 v82, v18, v18
	v_fmac_f32_e32 v83, v19, v19
	v_fmac_f32_e32 v82, v20, v20
	v_fmac_f32_e32 v83, v21, v21
	v_add_f32_e32 v82, v82, v83
	s_nop 1
	v_add_f32_dpp v82, v82, v82 row_ror:1 row_mask:0xf bank_mask:0xf
	s_nop 1
	v_add_f32_dpp v82, v82, v82 row_ror:2 row_mask:0xf bank_mask:0xf
	s_nop 1
	v_add_f32_dpp v82, v82, v82 row_ror:4 row_mask:0xf bank_mask:0xf
	s_nop 1
	v_add_f32_dpp v82, v82, v82 row_ror:8 row_mask:0xf bank_mask:0xf
	ds_swizzle_b32 v83, v82 offset:swizzle(SWAP,16)
	s_waitcnt lgkmcnt(0)
	v_add_f32_e32 v82, v82, v83
	v_mov_b32_e32 v83, v82
	s_nop 1
	v_permlane32_swap_b32_e32 v82, v83
	v_add_f32_e32 v82, v82, v83
	v_fmamk_f32 v82, v82, 0x3a800000, v218
	v_rsq_f32_e32 v82, v82
	s_nop 0
	v_pk_mul_f32 v[84:85], v[22:23], v[82:83] op_sel_hi:[1,0]
	v_pk_mul_f32 v[84:85], v[2:3], v[84:85]
	v_pk_mul_f32 v[86:87], v[24:25], v[82:83] op_sel_hi:[1,0]
	v_pk_mul_f32 v[86:87], v[4:5], v[86:87]
	v_cvt_pk_bf16_f32 v74, v84, v85
	v_cvt_pk_bf16_f32 v75, v86, v87
	v_pk_mul_f32 v[84:85], v[30:31], v[82:83] op_sel_hi:[1,0]
	v_pk_mul_f32 v[84:85], v[6:7], v[84:85]
	v_pk_mul_f32 v[86:87], v[32:33], v[82:83] op_sel_hi:[1,0]
	v_pk_mul_f32 v[86:87], v[8:9], v[86:87]
	v_cvt_pk_bf16_f32 v76, v84, v85
	v_cvt_pk_bf16_f32 v77, v86, v87
	v_pk_mul_f32 v[84:85], v[26:27], v[82:83] op_sel_hi:[1,0]
	v_pk_mul_f32 v[84:85], v[10:11], v[84:85]
	v_pk_mul_f32 v[86:87], v[28:29], v[82:83] op_sel_hi:[1,0]
	v_pk_mul_f32 v[86:87], v[12:13], v[86:87]
	v_cvt_pk_bf16_f32 v78, v84, v85
	v_cvt_pk_bf16_f32 v79, v86, v87
	v_pk_mul_f32 v[84:85], v[18:19], v[82:83] op_sel_hi:[1,0]
	v_pk_mul_f32 v[84:85], v[14:15], v[84:85]
	v_pk_mul_f32 v[86:87], v[20:21], v[82:83] op_sel_hi:[1,0]
	v_pk_mul_f32 v[86:87], v[16:17], v[86:87]
	v_cvt_pk_bf16_f32 v80, v84, v85
	v_cvt_pk_bf16_f32 v81, v86, v87
	s_add_i32 s2, s8, s4
	s_add_i32 s2, s2, s4
	s_cmp_lt_i32 s2, 0x10000
	s_cselect_b32 s10, s2, s8
	s_ashr_i32 s11, s10, 31
	s_lshl_b64 s[0:1], s[10:11], 12
	v_lshl_add_u64 v[72:73], v[34:35], 0, s[0:1]
	global_load_dwordx4 v[22:25], v[72:73], off
	global_load_dwordx4 v[30:33], v[72:73], off offset:1024
	global_load_dwordx4 v[26:29], v[72:73], off offset:2048
	global_load_dwordx4 v[18:21], v[72:73], off offset:3072
	global_store_dwordx2 v[36:37], v[74:75], off offset:-1024
	global_store_dwordx2 v[36:37], v[76:77], off offset:-512
	global_store_dwordx2 v[36:37], v[78:79], off
	global_store_dwordx2 v[36:37], v[80:81], off offset:512
	v_lshl_add_u64 v[36:37], v[36:37], 0, s[6:7]
	s_add_i32 s2, s8, s4
	s_cmp_lt_i32 s2, 0x10000
	s_cbranch_scc0 .Lrms_done
	s_waitcnt vmcnt(12)
	s_mov_b32 s8, s2
	v_mul_f32_e32 v82, v56, v56
	v_mul_f32_e32 v83, v57, v57
	v_fmac_f32_e32 v82, v58, v58
	v_fmac_f32_e32 v83, v59, v59
	v_fmac_f32_e32 v82, v60, v60
	v_fmac_f32_e32 v83, v61, v61
	v_fmac_f32_e32 v82, v62, v62
	v_fmac_f32_e32 v83, v63, v63
	v_fmac_f32_e32 v82, v64, v64
	v_fmac_f32_e32 v83, v65, v65
	v_fmac_f32_e32 v82, v66, v66
	v_fmac_f32_e32 v83, v67, v67
	v_fmac_f32_e32 v82, v68, v68
	v_fmac_f32_e32 v83, v69, v69
	v_fmac_f32_e32 v82, v70, v70
	v_fmac_f32_e32 v83, v71, v71
	v_add_f32_e32 v82, v82, v83
	s_nop 1
	v_add_f32_dpp v82, v82, v82 row_ror:1 row_mask:0xf bank_mask:0xf
	s_nop 1
	v_add_f32_dpp v82, v82, v82 row_ror:2 row_mask:0xf bank_mask:0xf
	s_nop 1
	v_add_f32_dpp v82, v82, v82 row_ror:4 row_mask:0xf bank_mask:0xf
	s_nop 1
	v_add_f32_dpp v82, v82, v82 row_ror:8 row_mask:0xf bank_mask:0xf
	ds_swizzle_b32 v83, v82 offset:swizzle(SWAP,16)
	s_waitcnt lgkmcnt(0)
	v_add_f32_e32 v82, v82, v83
	v_mov_b32_e32 v83, v82
	s_nop 1
	v_permlane32_swap_b32_e32 v82, v83
	v_add_f32_e32 v82, v82, v83
	v_fmamk_f32 v82, v82, 0x3a800000, v218
	v_rsq_f32_e32 v82, v82
	s_nop 0
	v_pk_mul_f32 v[84:85], v[56:57], v[82:83] op_sel_hi:[1,0]
	v_pk_mul_f32 v[84:85], v[2:3], v[84:85]
	v_pk_mul_f32 v[86:87], v[58:59], v[82:83] op_sel_hi:[1,0]
	v_pk_mul_f32 v[86:87], v[4:5], v[86:87]
	v_cvt_pk_bf16_f32 v74, v84, v85
	v_cvt_pk_bf16_f32 v75, v86, v87
	v_pk_mul_f32 v[84:85], v[60:61], v[82:83] op_sel_hi:[1,0]
	v_pk_mul_f32 v[84:85], v[6:7], v[84:85]
	v_pk_mul_f32 v[86:87], v[62:63], v[82:83] op_sel_hi:[1,0]
	v_pk_mul_f32 v[86:87], v[8:9], v[86:87]
	v_cvt_pk_bf16_f32 v76, v84, v85
	v_cvt_pk_bf16_f32 v77, v86, v87
	v_pk_mul_f32 v[84:85], v[64:65], v[82:83] op_sel_hi:[1,0]
	v_pk_mul_f32 v[84:85], v[10:11], v[84:85]
	v_pk_mul_f32 v[86:87], v[66:67], v[82:83] op_sel_hi:[1,0]
	v_pk_mul_f32 v[86:87], v[12:13], v[86:87]
	v_cvt_pk_bf16_f32 v78, v84, v85
	v_cvt_pk_bf16_f32 v79, v86, v87
	v_pk_mul_f32 v[84:85], v[68:69], v[82:83] op_sel_hi:[1,0]
	v_pk_mul_f32 v[84:85], v[14:15], v[84:85]
	v_pk_mul_f32 v[86:87], v[70:71], v[82:83] op_sel_hi:[1,0]
	v_pk_mul_f32 v[86:87], v[16:17], v[86:87]
	v_cvt_pk_bf16_f32 v80, v84, v85
	v_cvt_pk_bf16_f32 v81, v86, v87
	s_add_i32 s2, s8, s4
	s_add_i32 s2, s2, s4
	s_cmp_lt_i32 s2, 0x10000
	s_cselect_b32 s10, s2, s8
	s_ashr_i32 s11, s10, 31
	s_lshl_b64 s[0:1], s[10:11], 12
	v_lshl_add_u64 v[72:73], v[34:35], 0, s[0:1]
	global_load_dwordx4 v[56:59], v[72:73], off
	global_load_dwordx4 v[60:63], v[72:73], off offset:1024
	global_load_dwordx4 v[64:67], v[72:73], off offset:2048
	global_load_dwordx4 v[68:71], v[72:73], off offset:3072
	global_store_dwordx2 v[36:37], v[74:75], off offset:-1024
	global_store_dwordx2 v[36:37], v[76:77], off offset:-512
	global_store_dwordx2 v[36:37], v[78:79], off
	global_store_dwordx2 v[36:37], v[80:81], off offset:512
	v_lshl_add_u64 v[36:37], v[36:37], 0, s[6:7]
	s_add_i32 s8, s8, s4
	s_cmp_lt_i32 s8, 0x10000
	s_cbranch_scc1 .Lrms_loop
.Lrms_done:
.LBB0_131:
	s_barrier
	s_mov_b64 s[4:5], exec
	v_readlane_b32 s0, v254, 50
	v_readlane_b32 s1, v254, 51
	s_and_b64 s[0:1], s[4:5], s[0:1]
	s_mov_b64 exec, s[0:1]
	s_cbranch_execz .LBB0_141
	v_readlane_b32 s0, v254, 4
	v_readlane_b32 s1, v254, 5
	buffer_wbl2 sc1
	s_waitcnt vmcnt(0)
	s_load_dwordx2 s[6:7], s[0:1], 0x58
	s_mov_b64 s[8:9], exec
	v_mbcnt_lo_u32_b32 v2, s8, 0
	v_mbcnt_hi_u32_b32 v2, s9, v2
	v_cmp_eq_u32_e32 vcc, 0, v2
	s_waitcnt lgkmcnt(0)
	global_load_dword v0, v1, s[6:7] offset:40
	s_and_saveexec_b64 s[10:11], vcc
	s_cbranch_execz .LBB0_134
	s_bcnt1_i32_b64 s0, s[8:9]
	v_mov_b32_e32 v3, s0
	global_atomic_add v3, v1, v3, s[6:7] offset:32 sc0
